# S5 stage 3: causal Toeplitz fragments kept in registers per quarter, all LDS fragment reads issued up front, branch-free MFMA chain (zero fragments where masked)
# speedup vs baseline: 1.0134x; 1.0028x over previous
.LBB0_1393:
	v_add_u32_e32 v85, s4, v134
	s_nop 3
	ds_read_b128 v[88:91], v85
	ds_read_b128 v[92:95], v85 offset:4096
	s_addk_i32 s4, 0x200
	s_cmpk_lg_i32 s4, 0x800
	s_waitcnt lgkmcnt(1)
	v_mfma_f32_16x16x32_bf16 v[88:91], v[20:23], v[88:91], 0
	s_waitcnt lgkmcnt(0)
	v_mfma_f32_16x16x32_bf16 v[88:91], v[24:27], v[92:95], v[88:91]
	ds_read_b128 v[92:95], v85 offset:8192
	ds_read_b128 v[96:99], v85 offset:12288
	s_waitcnt lgkmcnt(1)
	v_mfma_f32_16x16x32_bf16 v[88:91], v[28:31], v[92:95], v[88:91]
	s_waitcnt lgkmcnt(0)
	v_mfma_f32_16x16x32_bf16 v[88:91], v[32:35], v[96:99], v[88:91]
	ds_read_b128 v[92:95], v85 offset:16384
	ds_read_b128 v[96:99], v85 offset:20480
	s_waitcnt lgkmcnt(1)
	v_mfma_f32_16x16x32_bf16 v[88:91], v[80:83], v[92:95], v[88:91]
	s_waitcnt lgkmcnt(0)
	v_mfma_f32_16x16x32_bf16 v[88:91], v[36:39], v[96:99], v[88:91]
	ds_read_b128 v[92:95], v85 offset:24576
	ds_read_b128 v[96:99], v85 offset:28672
	s_waitcnt lgkmcnt(1)
	v_mfma_f32_16x16x32_bf16 v[88:91], v[40:43], v[92:95], v[88:91]
	s_waitcnt lgkmcnt(0)
	v_mfma_f32_16x16x32_bf16 v[88:91], v[60:63], v[96:99], v[88:91]
	s_nop 7
	ds_write_b128 v84, v[88:91]
	v_add_u32_e32 v84, 0x2100, v84
	s_cbranch_scc1 .LBB0_1393
	s_waitcnt lgkmcnt(0)
	s_barrier
	ds_read_b64 v[88:89], v114 offset:8192
	ds_read2st64_b32 v[84:85], v117 offset1:1
	ds_read2st64_b32 v[90:91], v118 offset1:1
	ds_read2st64_b32 v[92:93], v119 offset1:1
	ds_read2st64_b32 v[94:95], v120 offset1:1
	ds_read2st64_b32 v[96:97], v121 offset1:1
	ds_read2st64_b32 v[98:99], v122 offset1:1
	ds_read2st64_b32 v[100:101], v123 offset1:1
	ds_read2st64_b32 v[102:103], v124 offset1:1
	s_waitcnt lgkmcnt(8)
	v_pk_mul_f32 v[156:157], v[88:89], 0 op_sel_hi:[1,0]
	v_readlane_b32 s4, v252, 10
	v_sub_f32_e32 v110, v156, v157
	s_waitcnt lgkmcnt(7)
	v_add_f32_e32 v158, v84, v110
	v_add_f32_e32 v84, v156, v157
	v_add_f32_e32 v160, v85, v84
	v_pk_mul_f32 v[84:85], v[88:89], v[160:161] op_sel:[1,0] op_sel_hi:[0,0]
	v_pk_fma_f32 v[110:111], v[88:89], v[158:159], v[84:85] neg_lo:[0,0,1] neg_hi:[0,0,1]
	v_pk_fma_f32 v[84:85], v[88:89], v[158:159], v[84:85] op_sel_hi:[1,0,1]
	v_readlane_b32 s5, v252, 11
	v_mov_b32_e32 v111, v85
	s_waitcnt lgkmcnt(6)
	v_pk_add_f32 v[162:163], v[90:91], v[110:111]
	v_mov_b32_e32 v159, v135
	v_pk_mul_f32 v[84:85], v[88:89], v[162:163]
	s_nop 0
	v_sub_f32_e32 v84, v84, v85
	s_waitcnt lgkmcnt(5)
	v_add_f32_e32 v164, v92, v84
	v_pk_mul_f32 v[84:85], v[88:89], v[162:163] op_sel:[0,1] op_sel_hi:[1,0]
	s_nop 0
	v_add_f32_e32 v84, v84, v85
	v_add_f32_e32 v166, v93, v84
	v_pk_mul_f32 v[84:85], v[88:89], v[166:167] op_sel_hi:[1,0]
	s_nop 0
	v_pk_fma_f32 v[90:91], v[88:89], v[164:165], v[84:85] op_sel:[1,0,0] op_sel_hi:[0,1,1]
	v_pk_fma_f32 v[84:85], v[88:89], v[164:165], v[84:85] op_sel:[1,0,0] op_sel_hi:[0,0,1] neg_lo:[0,0,1] neg_hi:[0,0,1]
	v_mov_b32_e32 v91, v85
	s_waitcnt lgkmcnt(4)
	v_mov_b32_e32 v84, v95
	v_mov_b32_e32 v85, v94
	v_pk_add_f32 v[168:169], v[84:85], v[90:91]
	s_nop 0
	v_pk_mul_f32 v[84:85], v[88:89], v[168:169] op_sel:[0,1] op_sel_hi:[1,0]
	s_nop 0
	v_sub_f32_e32 v84, v84, v85
	s_waitcnt lgkmcnt(3)
	v_add_f32_e32 v170, v96, v84
	v_pk_mul_f32 v[84:85], v[88:89], v[168:169]
	s_nop 0
	v_add_f32_e32 v84, v84, v85
	v_add_f32_e32 v172, v97, v84
	v_pk_mul_f32 v[84:85], v[88:89], v[172:173] op_sel_hi:[1,0]
	s_nop 0
	v_pk_fma_f32 v[90:91], v[88:89], v[170:171], v[84:85] op_sel:[1,0,0] op_sel_hi:[0,1,1]
	v_pk_fma_f32 v[84:85], v[88:89], v[170:171], v[84:85] op_sel:[1,0,0] op_sel_hi:[0,0,1] neg_lo:[0,0,1] neg_hi:[0,0,1]
	v_mov_b32_e32 v91, v85
	s_waitcnt lgkmcnt(2)
	v_mov_b32_e32 v84, v99
	v_mov_b32_e32 v85, v98
	v_pk_add_f32 v[174:175], v[84:85], v[90:91]
	s_nop 0
	v_pk_mul_f32 v[84:85], v[88:89], v[174:175] op_sel:[0,1] op_sel_hi:[1,0]
	s_nop 0
	v_sub_f32_e32 v84, v84, v85
	s_waitcnt lgkmcnt(1)
	v_add_f32_e32 v100, v100, v84
	v_pk_mul_f32 v[84:85], v[88:89], v[174:175]
	s_nop 0
	v_add_f32_e32 v84, v84, v85
	v_add_f32_e32 v90, v101, v84
	v_pk_mul_f32 v[84:85], v[88:89], v[90:91] op_sel:[1,0] op_sel_hi:[0,0]
	v_pk_fma_f32 v[92:93], v[88:89], v[100:101], v[84:85] neg_lo:[0,0,1] neg_hi:[0,0,1]
	v_pk_fma_f32 v[84:85], v[88:89], v[100:101], v[84:85] op_sel_hi:[1,0,1]
	s_nop 0
	v_mov_b32_e32 v93, v85
	s_waitcnt lgkmcnt(0)
	v_pk_add_f32 v[84:85], v[102:103], v[92:93]
	ds_write_b64 v115, v[84:85]
	v_pk_mul_f32 v[84:85], v[88:89], v[88:89]
	s_waitcnt lgkmcnt(0)
	v_sub_f32_e32 v84, v84, v85
	v_add_f32_e32 v85, v88, v88
	v_mul_f32_e32 v85, v89, v85
	v_mul_f32_e32 v91, v84, v84
	v_add_f32_e32 v84, v84, v84
	v_mul_f32_e32 v84, v85, v84
	v_fma_f32 v91, -v85, v85, v91
	v_mul_f32_e32 v85, v84, v84
	s_barrier
	ds_read2st64_b64 v[92:95], v116 offset1:1
	ds_read2st64_b64 v[96:99], v116 offset0:2 offset1:3
	v_fma_f32 v110, v91, v91, -v85
	v_add_f32_e32 v85, v91, v91
	v_mul_f32_e32 v112, v84, v85
	v_mul_f32_e32 v85, v86, v112
	v_mul_f32_e32 v84, v87, v112
	v_fmac_f32_e32 v85, v87, v110
	v_fma_f32 v84, v86, v110, -v84
	s_waitcnt lgkmcnt(1)
	v_add_f32_e32 v85, v85, v93
	v_add_f32_e32 v84, v84, v92
	v_mul_f32_e32 v91, v112, v85
	v_cndmask_b32_e64 v86, v86, v84, s[4:5]
	v_fma_f32 v91, v110, v84, -v91
	v_mul_f32_e32 v84, v112, v84
	v_cndmask_b32_e64 v87, v87, v85, s[4:5]
	v_fmac_f32_e32 v84, v110, v85
	v_readlane_b32 s4, v252, 12
	v_add_f32_e32 v91, v94, v91
	v_add_f32_e32 v84, v95, v84
	v_readlane_b32 s5, v252, 13
	ds_read2st64_b64 v[92:95], v116 offset0:4 offset1:5
	v_mov_b32_e32 v113, v112
	v_cndmask_b32_e64 v85, v86, v91, s[4:5]
	v_cndmask_b32_e64 v86, v87, v84, s[4:5]
	v_mul_f32_e32 v87, v112, v84
	v_fma_f32 v87, v110, v91, -v87
	v_mul_f32_e32 v91, v112, v91
	v_fmac_f32_e32 v91, v110, v84
	s_waitcnt lgkmcnt(1)
	v_add_f32_e32 v84, v97, v91
	v_add_f32_e32 v87, v96, v87
	v_mul_f32_e32 v91, v112, v84
	v_cndmask_b32_e64 v85, v85, v87, s[6:7]
	v_fma_f32 v91, v110, v87, -v91
	v_mul_f32_e32 v87, v112, v87
	v_fmac_f32_e32 v87, v110, v84
	v_cndmask_b32_e64 v86, v86, v84, s[6:7]
	v_add_f32_e32 v91, v98, v91
	v_add_f32_e32 v84, v99, v87
	v_cndmask_b32_e64 v98, v85, v91, s[8:9]
	v_mul_f32_e32 v85, v112, v84
	v_mul_f32_e32 v97, v112, v91
	v_fma_f32 v96, v110, v91, -v85
	v_fmac_f32_e32 v97, v110, v84
	v_cndmask_b32_e64 v99, v86, v84, s[8:9]
	ds_read2st64_b64 v[84:87], v116 offset0:6 offset1:7
	s_waitcnt lgkmcnt(1)
	v_pk_add_f32 v[92:93], v[92:93], v[96:97]
	v_mov_b32_e32 v111, v110
	v_pk_mul_f32 v[96:97], v[112:113], v[92:93] op_sel_hi:[0,1]
	v_cndmask_b32_e64 v91, v98, v92, s[10:11]
	v_cndmask_b32_e64 v101, v99, v93, s[10:11]
	v_pk_fma_f32 v[98:99], v[110:111], v[92:93], v[96:97] op_sel:[0,0,1] op_sel_hi:[1,1,0] neg_lo:[0,0,1] neg_hi:[0,0,1]
	v_pk_fma_f32 v[92:93], v[110:111], v[92:93], v[96:97] op_sel:[0,0,1] op_sel_hi:[0,1,0]
	v_mov_b32_e32 v99, v93
	v_pk_add_f32 v[92:93], v[94:95], v[98:99]
	s_mov_b64 s[4:5], 0
	v_pk_mul_f32 v[94:95], v[112:113], v[92:93] op_sel_hi:[0,1]
	v_cndmask_b32_e64 v91, v91, v92, s[12:13]
	v_cndmask_b32_e64 v98, v101, v93, s[12:13]
	v_pk_fma_f32 v[96:97], v[110:111], v[92:93], v[94:95] op_sel:[0,0,1] op_sel_hi:[1,1,0] neg_lo:[0,0,1] neg_hi:[0,0,1]
	v_pk_fma_f32 v[92:93], v[110:111], v[92:93], v[94:95] op_sel:[0,0,1] op_sel_hi:[0,1,0]
	v_mov_b32_e32 v97, v93
	s_waitcnt lgkmcnt(0)
	v_pk_add_f32 v[84:85], v[84:85], v[96:97]
	s_nop 0
	v_cndmask_b32_e64 v91, v91, v84, s[14:15]
	v_cndmask_b32_e64 v92, v98, v85, s[14:15]
	v_add_f32_e32 v93, 0, v91
	v_fmac_f32_e32 v93, 0x80000000, v92
	v_add_f32_e32 v94, 0, v92
	v_bfe_u32 v95, v93, 16, 1
	v_fmac_f32_e32 v94, 0, v91
	v_add3_u32 v93, v93, v95, s1
	ds_write_b16_d16_hi v125, v93
	v_bfe_u32 v93, v94, 16, 1
	v_add3_u32 v93, v94, v93, s1
	ds_write_b16_d16_hi v125, v93 offset:128
	v_sub_f32_e32 v93, v88, v157
	v_add_f32_e32 v94, v89, v156
	v_fmac_f32_e32 v158, v93, v91
	v_fma_f32 v95, -v94, v92, v158
	v_fmac_f32_e32 v160, v93, v92
	v_bfe_u32 v96, v95, 16, 1
	v_fmac_f32_e32 v160, v94, v91
	v_add3_u32 v95, v95, v96, s1
	ds_write_b16_d16_hi v126, v95
	v_bfe_u32 v95, v160, 16, 1
	v_add3_u32 v95, v160, v95, s1
	ds_write_b16_d16_hi v126, v95 offset:128
	v_mul_f32_e32 v95, v88, v93
	v_fma_f32 v95, -v89, v94, v95
	v_mul_f32_e32 v93, v89, v93
	v_fmac_f32_e32 v93, v88, v94
	v_fma_f32 v94, v95, v91, v162
	v_fma_f32 v94, -v93, v92, v94
	v_fmac_f32_e32 v163, v95, v92
	v_bfe_u32 v96, v94, 16, 1
	v_fmac_f32_e32 v163, v93, v91
	v_add3_u32 v94, v94, v96, s1
	ds_write_b16_d16_hi v127, v94
	v_bfe_u32 v94, v163, 16, 1
	v_add3_u32 v94, v163, v94, s1
	ds_write_b16_d16_hi v127, v94 offset:128
	v_mul_f32_e32 v94, v88, v95
	v_fma_f32 v94, -v89, v93, v94
	v_mul_f32_e32 v95, v89, v95
	v_fmac_f32_e32 v95, v88, v93
	v_fmac_f32_e32 v164, v94, v91
	v_fma_f32 v93, -v95, v92, v164
	v_fmac_f32_e32 v166, v94, v92
	v_bfe_u32 v96, v93, 16, 1
	v_fmac_f32_e32 v166, v95, v91
	v_add3_u32 v93, v93, v96, s1
	ds_write_b16_d16_hi v128, v93
	v_bfe_u32 v93, v166, 16, 1
	v_add3_u32 v93, v166, v93, s1
	ds_write_b16_d16_hi v128, v93 offset:128
	v_mul_f32_e32 v93, v88, v94
	v_fma_f32 v93, -v89, v95, v93
	v_mul_f32_e32 v94, v89, v94
	v_fmac_f32_e32 v94, v88, v95
	v_fma_f32 v95, v93, v91, v169
	v_fma_f32 v95, -v94, v92, v95
	v_fmac_f32_e32 v168, v93, v92
	v_bfe_u32 v96, v95, 16, 1
	v_fmac_f32_e32 v168, v94, v91
	v_add3_u32 v95, v95, v96, s1
	ds_write_b16_d16_hi v129, v95
	v_bfe_u32 v95, v168, 16, 1
	v_add3_u32 v95, v168, v95, s1
	ds_write_b16_d16_hi v129, v95 offset:128
	v_mul_f32_e32 v95, v88, v93
	v_fma_f32 v95, -v89, v94, v95
	v_mul_f32_e32 v93, v89, v93
	v_fmac_f32_e32 v93, v88, v94
	v_fmac_f32_e32 v170, v95, v91
	v_fma_f32 v94, -v93, v92, v170
	v_fmac_f32_e32 v172, v95, v92
	v_bfe_u32 v96, v94, 16, 1
	v_fmac_f32_e32 v172, v93, v91
	v_add3_u32 v94, v94, v96, s1
	ds_write_b16_d16_hi v130, v94
	v_bfe_u32 v94, v172, 16, 1
	v_add3_u32 v94, v172, v94, s1
	ds_write_b16_d16_hi v130, v94 offset:128
	v_mul_f32_e32 v94, v88, v95
	v_fma_f32 v94, -v89, v93, v94
	v_mul_f32_e32 v95, v89, v95
	v_fmac_f32_e32 v95, v88, v93
	v_fma_f32 v93, v94, v91, v175
	v_fma_f32 v93, -v95, v92, v93
	v_fmac_f32_e32 v174, v94, v92
	v_bfe_u32 v96, v93, 16, 1
	v_fmac_f32_e32 v174, v95, v91
	v_add3_u32 v93, v93, v96, s1
	ds_write_b16_d16_hi v131, v93
	v_bfe_u32 v93, v174, 16, 1
	v_add3_u32 v93, v174, v93, s1
	ds_write_b16_d16_hi v131, v93 offset:128
	v_mul_f32_e32 v93, v88, v94
	v_fma_f32 v93, -v89, v95, v93
	v_mul_f32_e32 v89, v89, v94
	v_fmac_f32_e32 v89, v88, v95
	v_fmac_f32_e32 v100, v93, v91
	v_fma_f32 v88, -v89, v92, v100
	v_fmac_f32_e32 v90, v93, v92
	v_fmac_f32_e32 v90, v89, v91
	v_bfe_u32 v89, v88, 16, 1
	v_add3_u32 v88, v88, v89, s1
	ds_write_b16_d16_hi v132, v88
	v_bfe_u32 v88, v90, 16, 1
	v_add3_u32 v88, v90, v88, s1
	v_mov_b32_e32 v156, v138
	v_mov_b32_e32 v157, v137
	v_mov_b32_e32 v158, v136
	ds_write_b16_d16_hi v132, v88 offset:128
	s_waitcnt lgkmcnt(0)
	s_barrier
	v_mov_b32_e32 v176, 0
	v_mov_b32_e32 v177, 0
	v_mov_b32_e32 v178, 0
	v_mov_b32_e32 v179, 0
	s_and_saveexec_b64 s[54:55], s[16:17]
	ds_read_b128 v[176:179], v140 offset:25088
	s_or_b64 exec, exec, s[54:55]
	v_mov_b32_e32 v180, 0
	v_mov_b32_e32 v181, 0
	v_mov_b32_e32 v182, 0
	v_mov_b32_e32 v183, 0
	s_and_saveexec_b64 s[54:55], s[20:21]
	ds_read_b128 v[180:183], v142 offset:25088
	s_or_b64 exec, exec, s[54:55]
	v_mov_b32_e32 v184, 0
	v_mov_b32_e32 v185, 0
	v_mov_b32_e32 v186, 0
	v_mov_b32_e32 v187, 0
	s_and_saveexec_b64 s[54:55], s[24:25]
	ds_read_b128 v[184:187], v144 offset:25088
	s_or_b64 exec, exec, s[54:55]
	v_mov_b32_e32 v188, 0
	v_mov_b32_e32 v189, 0
	v_mov_b32_e32 v190, 0
	v_mov_b32_e32 v191, 0
	s_and_saveexec_b64 s[54:55], s[28:29]
	ds_read_b128 v[188:191], v146 offset:25088
	s_or_b64 exec, exec, s[54:55]
	v_mov_b32_e32 v192, 0
	v_mov_b32_e32 v193, 0
	v_mov_b32_e32 v194, 0
	v_mov_b32_e32 v195, 0
	s_and_saveexec_b64 s[54:55], s[18:19]
	ds_read_b128 v[192:195], v141 offset:25088
	s_or_b64 exec, exec, s[54:55]
	v_mov_b32_e32 v196, 0
	v_mov_b32_e32 v197, 0
	v_mov_b32_e32 v198, 0
	v_mov_b32_e32 v199, 0
	s_and_saveexec_b64 s[54:55], s[22:23]
	ds_read_b128 v[196:199], v143 offset:25088
	s_or_b64 exec, exec, s[54:55]
	v_mov_b32_e32 v200, 0
	v_mov_b32_e32 v201, 0
	v_mov_b32_e32 v202, 0
	v_mov_b32_e32 v203, 0
	s_and_saveexec_b64 s[54:55], s[26:27]
	ds_read_b128 v[200:203], v145 offset:25088
	s_or_b64 exec, exec, s[54:55]
	v_mov_b32_e32 v204, 0
	v_mov_b32_e32 v205, 0
	v_mov_b32_e32 v206, 0
	v_mov_b32_e32 v207, 0
	s_and_saveexec_b64 s[54:55], s[30:31]
	ds_read_b128 v[204:207], v147 offset:25088
	s_or_b64 exec, exec, s[54:55]
	v_mov_b32_e32 v208, 0
	v_mov_b32_e32 v209, 0
	v_mov_b32_e32 v210, 0
	v_mov_b32_e32 v211, 0
	s_and_saveexec_b64 s[54:55], s[36:37]
	ds_read_b128 v[208:211], v149 offset:25088
	s_or_b64 exec, exec, s[54:55]
	v_mov_b32_e32 v212, 0
	v_mov_b32_e32 v213, 0
	v_mov_b32_e32 v214, 0
	v_mov_b32_e32 v215, 0
	s_and_saveexec_b64 s[54:55], s[40:41]
	ds_read_b128 v[212:215], v151 offset:25088
	s_or_b64 exec, exec, s[54:55]
	v_mov_b32_e32 v216, 0
	v_mov_b32_e32 v217, 0
	v_mov_b32_e32 v218, 0
	v_mov_b32_e32 v219, 0
	s_and_saveexec_b64 s[54:55], s[44:45]
	ds_read_b128 v[216:219], v153 offset:25088
	s_or_b64 exec, exec, s[54:55]
	v_mov_b32_e32 v220, 0
	v_mov_b32_e32 v221, 0
	v_mov_b32_e32 v222, 0
	v_mov_b32_e32 v223, 0
	s_and_saveexec_b64 s[54:55], s[48:49]
	ds_read_b128 v[220:223], v155 offset:25088
	s_or_b64 exec, exec, s[54:55]
	s_waitcnt lgkmcnt(0)
	s_branch .LBB0_1397

.Ls5_epi:
	s_nop 2
	v_add_u32_e32 v92, 0, v158
	ds_read_b64 v[94:95], v92
	v_add_u32_e32 v158, 0x200, v158
	s_waitcnt lgkmcnt(0)
	v_lshlrev_b32_e32 v92, 16, v94
	v_and_b32_e32 v93, 0xffff0000, v94
	v_pk_fma_f32 v[96:97], v[8:9], v[92:93], v[100:101]
	v_lshlrev_b32_e32 v94, 16, v95
	v_and_b32_e32 v93, 0x7fffffff, v97
	v_and_b32_e32 v92, 0x7fffffff, v96
	v_pk_fma_f32 v[92:93], v[92:93], s[80:81], 1.0 op_sel_hi:[1,0,0]
	v_and_b32_e32 v95, 0xffff0000, v95
	v_rcp_f32_e32 v98, v92
	v_rcp_f32_e32 v99, v93
	v_mov_b64_e32 v[92:93], s[54:55]
	v_cmp_gt_f32_e32 vcc, 0, v96
	v_pk_fma_f32 v[94:95], v[10:11], v[94:95], v[102:103]
	v_pk_fma_f32 v[100:101], v[98:99], s[50:51], v[92:93] op_sel_hi:[1,0,0]
	s_nop 0
	v_pk_fma_f32 v[100:101], v[98:99], v[100:101], s[76:77] op_sel_hi:[1,1,0]
	s_nop 0
	v_pk_fma_f32 v[100:101], v[98:99], v[100:101], s[78:79] op_sel_hi:[1,1,0]
	s_nop 0
	v_pk_fma_f32 v[100:101], v[98:99], v[100:101], s[2:3] op_sel_hi:[1,1,0]
	s_nop 0
	v_pk_mul_f32 v[98:99], v[98:99], v[100:101]
	v_pk_mul_f32 v[100:101], v[96:97], v[96:97]
	s_nop 0
	v_pk_mul_f32 v[100:101], v[100:101], s[0:1] op_sel_hi:[1,0]
	s_nop 0
	v_exp_f32_e32 v100, v100
	v_exp_f32_e32 v101, v101
	s_nop 0
	v_pk_mul_f32 v[98:99], v[100:101], v[98:99]
	s_nop 0
	v_pk_mul_f32 v[100:101], v[96:97], v[98:99]
	v_pk_fma_f32 v[98:99], v[96:97], v[98:99], v[96:97] neg_lo:[1,0,0] neg_hi:[1,0,0]
	v_and_b32_e32 v96, 0x7fffffff, v94
	v_cndmask_b32_e32 v100, v98, v100, vcc
	v_cmp_gt_f32_e32 vcc, 0, v97
	v_and_b32_e32 v97, 0x7fffffff, v95
	v_pk_fma_f32 v[96:97], v[96:97], s[80:81], 1.0 op_sel_hi:[1,0,0]
	v_cndmask_b32_e32 v101, v99, v101, vcc
	v_rcp_f32_e32 v96, v96
	v_rcp_f32_e32 v97, v97
	v_cmp_gt_f32_e32 vcc, 0, v94
	v_pk_fma_f32 v[98:99], v[96:97], s[50:51], v[92:93] op_sel_hi:[1,0,0]
	s_nop 0
	v_pk_fma_f32 v[98:99], v[96:97], v[98:99], s[76:77] op_sel_hi:[1,1,0]
	s_nop 0
	v_pk_fma_f32 v[98:99], v[96:97], v[98:99], s[78:79] op_sel_hi:[1,1,0]
	s_nop 0
	v_pk_fma_f32 v[98:99], v[96:97], v[98:99], s[2:3] op_sel_hi:[1,1,0]
	s_nop 0
	v_pk_mul_f32 v[96:97], v[96:97], v[98:99]
	v_pk_mul_f32 v[98:99], v[94:95], v[94:95]
	s_nop 0
	v_pk_mul_f32 v[98:99], v[98:99], s[0:1] op_sel_hi:[1,0]
	s_nop 0
	v_exp_f32_e32 v98, v98
	v_exp_f32_e32 v99, v99
	s_nop 0
	v_pk_mul_f32 v[96:97], v[98:99], v[96:97]
	s_nop 0
	v_pk_mul_f32 v[98:99], v[94:95], v[96:97]
	v_pk_fma_f32 v[96:97], v[94:95], v[96:97], v[94:95] neg_lo:[1,0,0] neg_hi:[1,0,0]
	v_cvt_pk_bf16_f32 v94, v100, v101
	s_nop 0
	v_cndmask_b32_e32 v96, v96, v98, vcc
	v_cmp_gt_f32_e32 vcc, 0, v95
	s_nop 1
	v_cndmask_b32_e32 v95, v97, v99, vcc
	v_cvt_pk_bf16_f32 v95, v96, v95
	v_lshl_add_u64 v[96:97], v[108:109], 0, s[4:5]
	global_store_dwordx2 v[96:97], v[94:95], off
	v_add_u32_e32 v94, 0, v159
	ds_read_b64 v[94:95], v94
	v_add_u32_e32 v159, 0x200, v159
	s_waitcnt lgkmcnt(0)
	v_lshlrev_b32_e32 v96, 16, v94
	v_and_b32_e32 v97, 0xffff0000, v94
	v_pk_fma_f32 v[88:89], v[8:9], v[96:97], v[88:89]
	s_nop 0
	v_and_b32_e32 v97, 0x7fffffff, v89
	v_and_b32_e32 v96, 0x7fffffff, v88
	v_pk_fma_f32 v[96:97], v[96:97], s[80:81], 1.0 op_sel_hi:[1,0,0]
	v_cmp_gt_f32_e32 vcc, 0, v88
	v_rcp_f32_e32 v96, v96
	v_rcp_f32_e32 v97, v97
	s_nop 0
	v_pk_fma_f32 v[98:99], v[96:97], s[50:51], v[92:93] op_sel_hi:[1,0,0]
	s_nop 0
	v_pk_fma_f32 v[98:99], v[96:97], v[98:99], s[76:77] op_sel_hi:[1,1,0]
	s_nop 0
	v_pk_fma_f32 v[98:99], v[96:97], v[98:99], s[78:79] op_sel_hi:[1,1,0]
	s_nop 0
	v_pk_fma_f32 v[98:99], v[96:97], v[98:99], s[2:3] op_sel_hi:[1,1,0]
	s_nop 0
	v_pk_mul_f32 v[96:97], v[96:97], v[98:99]
	v_pk_mul_f32 v[98:99], v[88:89], v[88:89]
	s_nop 0
	v_pk_mul_f32 v[98:99], v[98:99], s[0:1] op_sel_hi:[1,0]
	s_nop 0
	v_exp_f32_e32 v98, v98
	v_exp_f32_e32 v99, v99
	s_nop 0
	v_pk_mul_f32 v[96:97], v[98:99], v[96:97]
	s_nop 0
	v_pk_mul_f32 v[98:99], v[88:89], v[96:97]
	v_pk_fma_f32 v[96:97], v[88:89], v[96:97], v[88:89] neg_lo:[1,0,0] neg_hi:[1,0,0]
	v_lshlrev_b32_e32 v88, 16, v95
	v_cndmask_b32_e32 v94, v96, v98, vcc
	v_cmp_gt_f32_e32 vcc, 0, v89
	v_and_b32_e32 v89, 0xffff0000, v95
	v_pk_fma_f32 v[88:89], v[10:11], v[88:89], v[90:91]
	v_cndmask_b32_e32 v96, v97, v99, vcc
	v_and_b32_e32 v91, 0x7fffffff, v89
	v_and_b32_e32 v90, 0x7fffffff, v88
	v_pk_fma_f32 v[90:91], v[90:91], s[80:81], 1.0 op_sel_hi:[1,0,0]
	v_cmp_gt_f32_e32 vcc, 0, v88
	v_rcp_f32_e32 v90, v90
	v_rcp_f32_e32 v91, v91
	s_nop 0
	v_pk_fma_f32 v[92:93], v[90:91], s[50:51], v[92:93] op_sel_hi:[1,0,0]
	s_nop 0
	v_pk_fma_f32 v[92:93], v[90:91], v[92:93], s[76:77] op_sel_hi:[1,1,0]
	s_nop 0
	v_pk_fma_f32 v[92:93], v[90:91], v[92:93], s[78:79] op_sel_hi:[1,1,0]
	s_nop 0
	v_pk_fma_f32 v[92:93], v[90:91], v[92:93], s[2:3] op_sel_hi:[1,1,0]
	s_nop 0
	v_pk_mul_f32 v[90:91], v[90:91], v[92:93]
	v_pk_mul_f32 v[92:93], v[88:89], v[88:89]
	s_nop 0
	v_pk_mul_f32 v[92:93], v[92:93], s[0:1] op_sel_hi:[1,0]
	s_nop 0
	v_exp_f32_e32 v92, v92
	v_exp_f32_e32 v93, v93
	s_nop 0
	v_pk_mul_f32 v[90:91], v[92:93], v[90:91]
	s_nop 0
	v_pk_mul_f32 v[92:93], v[88:89], v[90:91]
	v_pk_fma_f32 v[90:91], v[88:89], v[90:91], v[88:89] neg_lo:[1,0,0] neg_hi:[1,0,0]
	v_cvt_pk_bf16_f32 v88, v94, v96
	s_nop 0
	v_cndmask_b32_e32 v90, v90, v92, vcc
	v_cmp_gt_f32_e32 vcc, 0, v89
	s_nop 1
	v_cndmask_b32_e32 v89, v91, v93, vcc
	v_cvt_pk_bf16_f32 v89, v90, v89
	v_lshl_add_u64 v[90:91], v[106:107], 0, s[4:5]
	s_add_u32 s4, s4, 0x100000
	s_addc_u32 s5, s5, 0
	s_cmp_eq_u32 s4, 0x400000
	global_store_dwordx2 v[90:91], v[88:89], off
	s_cbranch_scc1 .LBB0_1391
.LBB0_1397:
	v_add_u32_e32 v160, 0, v156
	ds_read_b128 v[224:227], v160
	ds_read_b128 v[228:231], v160 offset:4096
	ds_read_b128 v[232:235], v160 offset:8192
	ds_read_b128 v[236:239], v160 offset:12288
	ds_read_b128 v[240:243], v160 offset:16384
	ds_read_b128 v[244:247], v160 offset:20480
	ds_read_b128 v[248:251], v160 offset:24576
	ds_read_b128 v[100:103], v160 offset:28672
	v_add_u32_e32 v160, 0x18600, v157
	ds_read_b128 v[96:99], v160
	s_mov_b32 s53, s52
	s_mov_b32 s55, s52
	s_mov_b32 s54, 0xbf3a00e3
	v_add_u32_e32 v156, 0x200, v156
	v_add_u32_e32 v157, 0x1100, v157
	s_waitcnt lgkmcnt(0)
	v_mfma_f32_16x16x32_bf16 v[88:91], v[176:179], v[224:227], 0
	v_mfma_f32_16x16x32_bf16 v[92:95], v[192:195], v[224:227], 0
	ds_read_b128 v[224:227], v160 offset:64
	v_mfma_f32_16x16x32_bf16 v[88:91], v[180:183], v[228:231], v[88:91]
	v_mfma_f32_16x16x32_bf16 v[92:95], v[196:199], v[228:231], v[92:95]
	ds_read_b128 v[228:231], v160 offset:128
	v_mfma_f32_16x16x32_bf16 v[88:91], v[184:187], v[232:235], v[88:91]
	v_mfma_f32_16x16x32_bf16 v[92:95], v[200:203], v[232:235], v[92:95]
	ds_read_b128 v[232:235], v160 offset:192
	v_mfma_f32_16x16x32_bf16 v[88:91], v[188:191], v[236:239], v[88:91]
	v_mfma_f32_16x16x32_bf16 v[92:95], v[204:207], v[236:239], v[92:95]
	v_mfma_f32_16x16x32_bf16 v[92:95], v[208:211], v[240:243], v[92:95]
	v_mfma_f32_16x16x32_bf16 v[92:95], v[212:215], v[244:247], v[92:95]
	v_mfma_f32_16x16x32_bf16 v[92:95], v[216:219], v[248:251], v[92:95]
	v_mfma_f32_16x16x32_bf16 v[92:95], v[220:223], v[100:103], v[92:95]
	s_waitcnt lgkmcnt(0)
	v_mfma_f32_16x16x32_bf16 v[88:91], v[44:47], v[96:99], v[88:91]
	v_mfma_f32_16x16x32_bf16 v[92:95], v[64:67], v[96:99], v[92:95]
	v_mfma_f32_16x16x32_bf16 v[88:91], v[48:51], v[224:227], v[88:91]
	v_mfma_f32_16x16x32_bf16 v[92:95], v[68:71], v[224:227], v[92:95]
	v_mfma_f32_16x16x32_bf16 v[88:91], v[52:55], v[228:231], v[88:91]
	v_mfma_f32_16x16x32_bf16 v[92:95], v[72:75], v[228:231], v[92:95]
	v_mfma_f32_16x16x32_bf16 v[100:103], v[56:59], v[232:235], v[88:91]
	v_mfma_f32_16x16x32_bf16 v[88:91], v[76:79], v[232:235], v[92:95]
	s_branch .Ls5_epi
